# indexer items remapped so the 8 waves of a workgroup share a batch and adjacent query pairs (key blocks hit in L1)
# speedup vs baseline: 1.0025x; 1.0025x over previous
; DI float bf2f(unsigned b) { return __uint_as_float(b << 16); }
; DI void indexer_phase(const u16* __restrict__ P, unsigned* __restrict__ mask) {
;     ...
;   for (int base = 0, pass = 0; base < 8192; base += nw, ++pass) {
;     const int item = (pass & 1) ? base + (nw - 1 - gw) : base + gw;
;     if (item >= 8192) continue;
;     const int b = item & 7, t0 = (1023 - (item >> 3)) * 2;
;     const size_t brow = (size_t)b * SEQ;
;     const int g = (r32 >> 2) & 1, head = 4 * (r32 >> 3) + (r32 & 3);
;     bf16x8 aq[4];
; #pragma unroll
;     for (int s = 0; s < 4; ++s) aq[s] = *(const bf16x8*)(P + (brow + t0 + g) * 7808 + 2560 + head * 64 + 16 * s + 8 * hi);
;     float wv[16];
;     {
;       const u32x4 w0 = *(const u32x4*)(P + (brow + t0 + hi) * 7808 + 3648), w1 = *(const u32x4*)(P + (brow + t0 + hi) * 7808 + 3656);
; #pragma unroll
;       for (int j = 0; j < 4; ++j) { wv[2 * j] = bf2f(w0[j] & 0xffffu); wv[2 * j + 1] = bf2f(w0[j] >> 16); wv[8 + 2 * j] = bf2f(w1[j] & 0xffffu); wv[8 + 2 * j + 1] = bf2f(w1[j] >> 16); }
;     }
;     const int tme = t0 + hi, kbmax = (t0 + 1) >> 5;
.LBB0_846:
	s_bitcmp0_b32 s87, 0
	s_cselect_b64 vcc, -1, 0
	v_cndmask_b32_e32 v2, v55, v53, vcc
	v_add_u32_e32 v3, s89, v2
	v_cmp_gt_i32_e32 vcc, s2, v3
	s_and_saveexec_b64 s[8:9], vcc
	s_cbranch_execz .LBB0_845
	v_and_b32_e32 v2, 7, v3
	v_ashrrev_i32_e32 v3, 3, v3
	v_and_b32_e32 v126, 7, v3
	v_and_or_b32 v3, v3, -8, v2
	v_lshlrev_b32_e32 v126, 11, v126
	v_lshlrev_b32_e32 v3, 1, v3
	v_sub_u32_e32 v144, 0x7fe, v3
	v_add_u32_e32 v8, v144, v126
	v_or_b32_e32 v4, v8, v52
	v_mov_b64_e32 v[2:3], s[96:97]
	s_movk_i32 s23, 0x3d00
	v_mad_u64_u32 v[4:5], s[0:1], v4, s23, v[2:3]
	v_lshl_add_u64 v[4:5], v[4:5], 0, v[0:1]
	v_lshlrev_b32_e32 v60, 1, v54
	v_mov_b32_e32 v61, v1
	v_lshl_add_u64 v[4:5], v[4:5], 0, v[60:61]
	s_mov_b64 s[0:1], 0x1400
	s_movk_i32 s22, 0x1000
	v_lshl_add_u64 v[6:7], v[4:5], 0, s[0:1]
	v_add_co_u32_e32 v4, vcc, s22, v4
	v_writelane_b32 v255, s8, 56
	s_nop 0
	v_addc_co_u32_e32 v5, vcc, 0, v5, vcc
	global_load_dwordx4 v[46:49], v[4:5], off offset:1024
	global_load_dwordx4 v[42:45], v[6:7], off offset:32
	global_load_dwordx4 v[38:41], v[6:7], off offset:64
	global_load_dwordx4 v[34:37], v[6:7], off offset:96
	v_or_b32_e32 v4, v8, v50
	v_mad_u64_u32 v[2:3], s[0:1], v4, s23, v[2:3]
	s_mov_b64 s[0:1], 0x1c80
	s_nop 0
	v_lshl_add_u64 v[6:7], v[2:3], 0, s[0:1]
	v_add_co_u32_e32 v2, vcc, s22, v2
	s_mov_b64 s[0:1], 0x1c00
	s_nop 0
	v_addc_co_u32_e32 v3, vcc, 0, v3, vcc
	global_load_dwordx4 v[2:5], v[2:3], off offset:3200
	s_nop 0
	global_load_dwordx4 v[6:9], v[6:7], off offset:16
	v_writelane_b32 v255, s9, 57
	v_or_b32_e32 v127, v144, v50
	s_brev_b32 s8, 1
	v_mul_u32_u24_e32 v10, 0x1e80, v126
	v_readfirstlane_b32 s0, v144
	v_lshlrev_b32_e32 v10, 1, v10
	v_readfirstlane_b32 s1, v179
	v_add_u32_e32 v10, 0x1c00, v10
	v_mov_b32_e32 v11, v1
	v_lshl_add_u64 v[10:11], s[96:97], 0, v[10:11]
	s_lshr_b32 s1, s1, 6
	v_and_b32_e32 v12, 63, v179
	v_readfirstlane_b32 s22, v10
	v_readfirstlane_b32 s23, v11
	s_lshl_b32 s1, s1, 14
	v_lshrrev_b32_e32 v13, 3, v12
	v_lshrrev_b32_e32 v14, 4, v12
	v_mul_u32_u24_e32 v13, 0x3d00, v13
	v_xor_b32_e32 v14, v14, v12
	v_and_b32_e32 v14, 7, v14
	v_lshl_add_u32 v112, v14, 4, v13
	v_xor_b32_e32 v113, 64, v112
	v_bfe_u32 v13, v12, 1, 3
	v_xor_b32_e32 v13, v13, v50
	v_lshlrev_b32_e32 v13, 4, v13
	v_lshl_add_u32 v13, v51, 7, v13
	v_add_u32_e32 v114, s1, v13
	v_xor_b32_e32 v115, 32, v114
	v_xor_b32_e32 v116, 64, v114
	v_xor_b32_e32 v117, 0x60, v114
	v_sub_u32_e32 v16, v127, v51
	s_add_u32 m0, s1, 0
	s_nop 0
	global_load_lds_dwordx4 v112, s[22:23]
	s_add_u32 s22, s22, 0x1e800
	s_addc_u32 s23, s23, 0
	s_add_u32 m0, s1, 0x400
	s_nop 0
	global_load_lds_dwordx4 v113, s[22:23]
	s_add_u32 s22, s22, 0x1e800
	s_addc_u32 s23, s23, 0
	s_add_u32 m0, s1, 0x800
	s_nop 0
	global_load_lds_dwordx4 v112, s[22:23]
	s_add_u32 s22, s22, 0x1e800
	s_addc_u32 s23, s23, 0
	s_add_u32 m0, s1, 0xc00
	s_nop 0
	global_load_lds_dwordx4 v113, s[22:23]
	s_add_u32 s22, s22, 0x1e800
	s_addc_u32 s23, s23, 0
	s_cmp_lt_u32 s0, 32
	s_cbranch_scc1 .Lix_pro_done
	s_add_u32 m0, s1, 0x1000
	s_nop 0
	global_load_lds_dwordx4 v112, s[22:23]
	s_add_u32 s22, s22, 0x1e800
	s_addc_u32 s23, s23, 0
	s_add_u32 m0, s1, 0x1400
	s_nop 0
	global_load_lds_dwordx4 v113, s[22:23]
	s_add_u32 s22, s22, 0x1e800
	s_addc_u32 s23, s23, 0
	s_add_u32 m0, s1, 0x1800
	s_nop 0
	global_load_lds_dwordx4 v112, s[22:23]
	s_add_u32 s22, s22, 0x1e800
	s_addc_u32 s23, s23, 0
	s_add_u32 m0, s1, 0x1c00
	s_nop 0
	global_load_lds_dwordx4 v113, s[22:23]
	s_add_u32 s22, s22, 0x1e800
	s_addc_u32 s23, s23, 0
	s_cmp_lt_u32 s0, 64
	s_cbranch_scc1 .Lix_pro_done
	s_add_u32 m0, s1, 0x2000
	s_nop 0
	global_load_lds_dwordx4 v112, s[22:23]
	s_add_u32 s22, s22, 0x1e800
	s_addc_u32 s23, s23, 0
	s_add_u32 m0, s1, 0x2400
	s_nop 0
	global_load_lds_dwordx4 v113, s[22:23]
	s_add_u32 s22, s22, 0x1e800
	s_addc_u32 s23, s23, 0
	s_add_u32 m0, s1, 0x2800
	s_nop 0
	global_load_lds_dwordx4 v112, s[22:23]
	s_add_u32 s22, s22, 0x1e800
	s_addc_u32 s23, s23, 0
	s_add_u32 m0, s1, 0x2c00
	s_nop 0
	global_load_lds_dwordx4 v113, s[22:23]
	s_add_u32 s22, s22, 0x1e800
	s_addc_u32 s23, s23, 0
